# P1 and P4 K-loop heads also aligned to a 64-byte instruction line, on top of v076
# baseline (speedup 1.0000x reference)
.LBB0_122:
	s_add_u32 s0, s0, 0x80080
	s_addc_u32 s1, s1, 0
	s_add_u32 s65, s4, 0x100
	v_mov_b32_e32 v0, 0
	s_addc_u32 s67, s5, 0
	s_mov_b32 s78, -2
	v_mov_b32_e32 v1, v0
	v_mov_b32_e32 v2, v0
	v_mov_b32_e32 v3, v0
	v_mov_b32_e32 v4, v0
	v_mov_b32_e32 v5, v0
	v_mov_b32_e32 v6, v0
	v_mov_b32_e32 v7, v0
	v_mov_b32_e32 v16, v0
	v_mov_b32_e32 v17, v0
	v_mov_b32_e32 v18, v0
	v_mov_b32_e32 v19, v0
	v_mov_b32_e32 v20, v0
	v_mov_b32_e32 v21, v0
	v_mov_b32_e32 v22, v0
	v_mov_b32_e32 v23, v0
	v_mov_b32_e32 v32, v0
	v_mov_b32_e32 v33, v0
	v_mov_b32_e32 v34, v0
	v_mov_b32_e32 v35, v0
	v_mov_b32_e32 v36, v0
	v_mov_b32_e32 v37, v0
	v_mov_b32_e32 v38, v0
	v_mov_b32_e32 v39, v0
	v_mov_b32_e32 v48, v0
	v_mov_b32_e32 v49, v0
	v_mov_b32_e32 v50, v0
	v_mov_b32_e32 v51, v0
	v_mov_b32_e32 v52, v0
	v_mov_b32_e32 v53, v0
	v_mov_b32_e32 v54, v0
	v_mov_b32_e32 v55, v0
	v_mov_b32_e32 v8, v0
	v_mov_b32_e32 v9, v0
	v_mov_b32_e32 v10, v0
	v_mov_b32_e32 v11, v0
	v_mov_b32_e32 v12, v0
	v_mov_b32_e32 v13, v0
	v_mov_b32_e32 v14, v0
	v_mov_b32_e32 v15, v0
	v_mov_b32_e32 v24, v0
	v_mov_b32_e32 v25, v0
	v_mov_b32_e32 v26, v0
	v_mov_b32_e32 v27, v0
	v_mov_b32_e32 v28, v0
	v_mov_b32_e32 v29, v0
	v_mov_b32_e32 v30, v0
	v_mov_b32_e32 v31, v0
	v_mov_b32_e32 v40, v0
	v_mov_b32_e32 v41, v0
	v_mov_b32_e32 v42, v0
	v_mov_b32_e32 v43, v0
	v_mov_b32_e32 v44, v0
	v_mov_b32_e32 v45, v0
	v_mov_b32_e32 v46, v0
	v_mov_b32_e32 v47, v0
	v_mov_b32_e32 v56, v0
	v_mov_b32_e32 v57, v0
	v_mov_b32_e32 v58, v0
	v_mov_b32_e32 v59, v0
	v_mov_b32_e32 v60, v0
	v_mov_b32_e32 v61, v0
	v_mov_b32_e32 v62, v0
	v_mov_b32_e32 v63, v0
	v_mov_b32_e32 v64, v0
	v_mov_b32_e32 v65, v0
	v_mov_b32_e32 v66, v0
	v_mov_b32_e32 v67, v0
	v_mov_b32_e32 v68, v0
	v_mov_b32_e32 v69, v0
	v_mov_b32_e32 v70, v0
	v_mov_b32_e32 v71, v0
	v_mov_b32_e32 v80, v0
	v_mov_b32_e32 v81, v0
	v_mov_b32_e32 v82, v0
	v_mov_b32_e32 v83, v0
	v_mov_b32_e32 v84, v0
	v_mov_b32_e32 v85, v0
	v_mov_b32_e32 v86, v0
	v_mov_b32_e32 v87, v0
	v_mov_b32_e32 v96, v0
	v_mov_b32_e32 v97, v0
	v_mov_b32_e32 v98, v0
	v_mov_b32_e32 v99, v0
	v_mov_b32_e32 v100, v0
	v_mov_b32_e32 v101, v0
	v_mov_b32_e32 v102, v0
	v_mov_b32_e32 v103, v0
	v_mov_b32_e32 v112, v0
	v_mov_b32_e32 v113, v0
	v_mov_b32_e32 v114, v0
	v_mov_b32_e32 v115, v0
	v_mov_b32_e32 v116, v0
	v_mov_b32_e32 v117, v0
	v_mov_b32_e32 v118, v0
	v_mov_b32_e32 v119, v0
	v_mov_b32_e32 v72, v0
	v_mov_b32_e32 v73, v0
	v_mov_b32_e32 v74, v0
	v_mov_b32_e32 v75, v0
	v_mov_b32_e32 v76, v0
	v_mov_b32_e32 v77, v0
	v_mov_b32_e32 v78, v0
	v_mov_b32_e32 v79, v0
	v_mov_b32_e32 v88, v0
	v_mov_b32_e32 v89, v0
	v_mov_b32_e32 v90, v0
	v_mov_b32_e32 v91, v0
	v_mov_b32_e32 v92, v0
	v_mov_b32_e32 v93, v0
	v_mov_b32_e32 v94, v0
	v_mov_b32_e32 v95, v0
	v_mov_b32_e32 v104, v0
	v_mov_b32_e32 v105, v0
	v_mov_b32_e32 v106, v0
	v_mov_b32_e32 v107, v0
	v_mov_b32_e32 v108, v0
	v_mov_b32_e32 v109, v0
	v_mov_b32_e32 v110, v0
	v_mov_b32_e32 v111, v0
	v_mov_b32_e32 v120, v0
	v_mov_b32_e32 v121, v0
	v_mov_b32_e32 v122, v0
	v_mov_b32_e32 v123, v0
	v_mov_b32_e32 v124, v0
	v_mov_b32_e32 v125, v0
	v_mov_b32_e32 v126, v0
	v_mov_b32_e32 v127, v0
	.p2align 6

.LBB0_412:
	s_add_u32 s50, s50, 0x80080
	s_addc_u32 s51, s51, 0
	s_add_u32 s23, s52, 0x100
	v_mov_b32_e32 v0, 0
	s_addc_u32 s25, s53, 0
	s_mov_b32 s45, -2
	s_waitcnt lgkmcnt(0)
	v_mov_b32_e32 v1, v0
	v_mov_b32_e32 v2, v0
	v_mov_b32_e32 v3, v0
	v_mov_b32_e32 v4, v0
	v_mov_b32_e32 v5, v0
	v_mov_b32_e32 v6, v0
	v_mov_b32_e32 v7, v0
	v_mov_b32_e32 v16, v0
	v_mov_b32_e32 v17, v0
	v_mov_b32_e32 v18, v0
	v_mov_b32_e32 v19, v0
	v_mov_b32_e32 v20, v0
	v_mov_b32_e32 v21, v0
	v_mov_b32_e32 v22, v0
	v_mov_b32_e32 v23, v0
	v_mov_b32_e32 v32, v0
	v_mov_b32_e32 v33, v0
	v_mov_b32_e32 v34, v0
	v_mov_b32_e32 v35, v0
	v_mov_b32_e32 v36, v0
	v_mov_b32_e32 v37, v0
	v_mov_b32_e32 v38, v0
	v_mov_b32_e32 v39, v0
	v_mov_b32_e32 v48, v0
	v_mov_b32_e32 v49, v0
	v_mov_b32_e32 v50, v0
	v_mov_b32_e32 v51, v0
	v_mov_b32_e32 v52, v0
	v_mov_b32_e32 v53, v0
	v_mov_b32_e32 v54, v0
	v_mov_b32_e32 v55, v0
	v_mov_b32_e32 v8, v0
	v_mov_b32_e32 v9, v0
	v_mov_b32_e32 v10, v0
	v_mov_b32_e32 v11, v0
	v_mov_b32_e32 v12, v0
	v_mov_b32_e32 v13, v0
	v_mov_b32_e32 v14, v0
	v_mov_b32_e32 v15, v0
	v_mov_b32_e32 v24, v0
	v_mov_b32_e32 v25, v0
	v_mov_b32_e32 v26, v0
	v_mov_b32_e32 v27, v0
	v_mov_b32_e32 v28, v0
	v_mov_b32_e32 v29, v0
	v_mov_b32_e32 v30, v0
	v_mov_b32_e32 v31, v0
	v_mov_b32_e32 v40, v0
	v_mov_b32_e32 v41, v0
	v_mov_b32_e32 v42, v0
	v_mov_b32_e32 v43, v0
	v_mov_b32_e32 v44, v0
	v_mov_b32_e32 v45, v0
	v_mov_b32_e32 v46, v0
	v_mov_b32_e32 v47, v0
	v_mov_b32_e32 v56, v0
	v_mov_b32_e32 v57, v0
	v_mov_b32_e32 v58, v0
	v_mov_b32_e32 v59, v0
	v_mov_b32_e32 v60, v0
	v_mov_b32_e32 v61, v0
	v_mov_b32_e32 v62, v0
	v_mov_b32_e32 v63, v0
	v_mov_b32_e32 v64, v0
	v_mov_b32_e32 v65, v0
	v_mov_b32_e32 v66, v0
	v_mov_b32_e32 v67, v0
	v_mov_b32_e32 v68, v0
	v_mov_b32_e32 v69, v0
	v_mov_b32_e32 v70, v0
	v_mov_b32_e32 v71, v0
	v_mov_b32_e32 v80, v0
	v_mov_b32_e32 v81, v0
	v_mov_b32_e32 v82, v0
	v_mov_b32_e32 v83, v0
	v_mov_b32_e32 v84, v0
	v_mov_b32_e32 v85, v0
	v_mov_b32_e32 v86, v0
	v_mov_b32_e32 v87, v0
	v_mov_b32_e32 v96, v0
	v_mov_b32_e32 v97, v0
	v_mov_b32_e32 v98, v0
	v_mov_b32_e32 v99, v0
	v_mov_b32_e32 v100, v0
	v_mov_b32_e32 v101, v0
	v_mov_b32_e32 v102, v0
	v_mov_b32_e32 v103, v0
	v_mov_b32_e32 v112, v0
	v_mov_b32_e32 v113, v0
	v_mov_b32_e32 v114, v0
	v_mov_b32_e32 v115, v0
	v_mov_b32_e32 v116, v0
	v_mov_b32_e32 v117, v0
	v_mov_b32_e32 v118, v0
	v_mov_b32_e32 v119, v0
	v_mov_b32_e32 v72, v0
	v_mov_b32_e32 v73, v0
	v_mov_b32_e32 v74, v0
	v_mov_b32_e32 v75, v0
	v_mov_b32_e32 v76, v0
	v_mov_b32_e32 v77, v0
	v_mov_b32_e32 v78, v0
	v_mov_b32_e32 v79, v0
	v_mov_b32_e32 v88, v0
	v_mov_b32_e32 v89, v0
	v_mov_b32_e32 v90, v0
	v_mov_b32_e32 v91, v0
	v_mov_b32_e32 v92, v0
	v_mov_b32_e32 v93, v0
	v_mov_b32_e32 v94, v0
	v_mov_b32_e32 v95, v0
	v_mov_b32_e32 v104, v0
	v_mov_b32_e32 v105, v0
	v_mov_b32_e32 v106, v0
	v_mov_b32_e32 v107, v0
	v_mov_b32_e32 v108, v0
	v_mov_b32_e32 v109, v0
	v_mov_b32_e32 v110, v0
	v_mov_b32_e32 v111, v0
	v_mov_b32_e32 v120, v0
	v_mov_b32_e32 v121, v0
	v_mov_b32_e32 v122, v0
	v_mov_b32_e32 v123, v0
	v_mov_b32_e32 v124, v0
	v_mov_b32_e32 v125, v0
	v_mov_b32_e32 v126, v0
	v_mov_b32_e32 v127, v0
	.p2align 6
